# scan loader: gate loads double-buffered one iteration ahead (no exposed memory latency in the epilogue); on top of P2 forward-substitution read pipelining
# baseline (speedup 1.0000x reference)
.LBB0_555:
	s_or_b64 exec, exec, s[0:1]
	s_mov_b64 s[0:1], -1
	s_cmp_gt_i32 s98, 3
	s_mul_hi_i32 s3, s99, 0x84000
	s_mul_i32 s33, s99, 0x84000
	s_cbranch_scc0 .LBB0_589
	s_mul_hi_i32 s5, s99, 0x42000
	s_mul_i32 s4, s99, 0x42000
	s_ashr_i32 s0, s99, 3
	s_lshl_b64 s[14:15], s[4:5], 1
	s_add_u32 s54, s72, s14
	s_waitcnt vmcnt(0)
	v_lshlrev_b32_e32 v32, 4, v154
	s_addc_u32 s55, s73, s15
	v_and_b32_e32 v128, 0xf0, v32
	v_lshl_add_u64 v[0:1], s[54:55], 0, v[128:129]
	s_add_u32 s54, s76, s14
	s_addc_u32 s55, s77, s15
	s_add_u32 s14, s74, s14
	v_and_b32_e32 v8, 0xf00, v32
	v_mov_b32_e32 v9, v129
	v_lshl_add_u64 v[2:3], s[54:55], 0, v[128:129]
	s_addc_u32 s15, s75, s15
	v_lshl_add_u64 v[6:7], v[0:1], 0, v[8:9]
	v_lshl_add_u64 v[4:5], s[14:15], 0, v[128:129]
	global_load_dwordx4 v[10:13], v[6:7], off
	v_lshl_add_u64 v[6:7], v[2:3], 0, v[8:9]
	global_load_dwordx4 v[14:17], v[6:7], off
	v_lshl_add_u64 v[6:7], v[4:5], 0, v[8:9]
	v_or_b32_e32 v20, 0x1000, v8
	v_mov_b32_e32 v21, v129
	v_lshl_add_u64 v[18:19], v[0:1], 0, v[20:21]
	global_load_dwordx4 v[24:27], v[6:7], off
	global_load_dwordx4 v[36:39], v[18:19], off
	v_lshl_add_u64 v[6:7], v[2:3], 0, v[20:21]
	global_load_dwordx4 v[40:43], v[6:7], off
	v_lshl_add_u64 v[6:7], v[4:5], 0, v[20:21]
	v_or_b32_e32 v22, 0x2000, v8
	v_mov_b32_e32 v23, v129
	v_lshl_add_u64 v[18:19], v[0:1], 0, v[22:23]
	global_load_dwordx4 v[44:47], v[6:7], off
	global_load_dwordx4 v[48:51], v[18:19], off
	v_lshl_add_u64 v[6:7], v[2:3], 0, v[22:23]
	v_or_b32_e32 v28, 0x3000, v8
	v_mov_b32_e32 v29, v129
	global_load_dwordx4 v[52:55], v[6:7], off
	v_lshl_add_u64 v[6:7], v[4:5], 0, v[22:23]
	v_lshl_add_u64 v[18:19], v[0:1], 0, v[28:29]
	global_load_dwordx4 v[56:59], v[6:7], off
	global_load_dwordx4 v[60:63], v[18:19], off
	s_add_u32 s14, s78, s4
	v_lshl_add_u64 v[18:19], v[2:3], 0, s[38:39]
	v_lshl_add_u64 v[6:7], v[2:3], 0, v[28:29]
	s_addc_u32 s15, s79, s5
	v_and_b32_e32 v72, 0x70, v32
	v_mov_b32_e32 v73, v129
	v_lshl_add_u64 v[90:91], v[4:5], 0, s[38:39]
	v_lshl_add_u64 v[86:87], v[18:19], 0, v[8:9]
	global_load_dwordx4 v[64:67], v[6:7], off
	v_lshl_add_u64 v[30:31], s[14:15], 0, v[72:73]
	v_and_b32_e32 v32, 0xf80, v32
	v_mov_b32_e32 v33, v129
	global_load_dwordx4 v[86:89], v[86:87], off
	v_lshl_add_u64 v[6:7], v[4:5], 0, v[28:29]
	v_lshl_add_u64 v[92:93], v[90:91], 0, v[8:9]
	global_load_dwordx4 v[68:71], v[6:7], off
	v_or_b32_e32 v34, 0x1000, v32
	v_mov_b32_e32 v35, v129
	global_load_dwordx4 v[92:95], v[92:93], off
	v_lshl_add_u64 v[6:7], v[30:31], 0, v[32:33]
	v_lshl_add_u64 v[100:101], v[18:19], 0, v[20:21]
	global_load_dwordx4 v[74:77], v[6:7], off
	v_lshl_add_u64 v[104:105], v[90:91], 0, v[20:21]
	global_load_dwordx4 v[100:103], v[100:101], off
	v_lshl_add_u64 v[6:7], v[30:31], 0, v[34:35]
	global_load_dwordx4 v[78:81], v[6:7], off
	v_lshl_add_u64 v[6:7], v[0:1], 0, s[38:39]
	v_lshl_add_u64 v[82:83], v[6:7], 0, v[8:9]
	global_load_dwordx4 v[82:85], v[82:83], off
	v_lshl_add_u64 v[96:97], v[6:7], 0, v[20:21]
	global_load_dwordx4 v[96:99], v[96:97], off
	v_lshl_add_u64 v[108:109], v[6:7], 0, v[22:23]
	v_lshl_add_u64 v[112:113], v[18:19], 0, v[22:23]
	v_lshl_add_u64 v[6:7], v[6:7], 0, v[28:29]
	global_load_dwordx4 v[104:107], v[104:105], off
	v_lshl_add_u64 v[116:117], v[90:91], 0, v[22:23]
	global_load_dwordx4 v[112:115], v[112:113], off
	v_bfe_u32 v142, v154, 4, 4
	global_load_dwordx4 v[120:123], v[6:7], off
	v_lshl_add_u64 v[6:7], v[18:19], 0, v[28:29]
	global_load_dwordx4 v[108:111], v[108:109], off
	s_movk_i32 s1, 0x100
	global_load_dwordx4 v[116:119], v[116:117], off
	v_bfe_u32 v156, v154, 3, 5
	global_load_dwordx4 v[124:127], v[6:7], off
	v_lshl_add_u64 v[6:7], v[90:91], 0, v[28:29]
	global_load_dwordx4 v[130:133], v[6:7], off
	v_lshl_add_u64 v[6:7], v[30:31], 0, s[36:37]
	v_lshl_add_u64 v[18:19], v[6:7], 0, v[32:33]
	v_lshl_add_u64 v[6:7], v[6:7], 0, v[34:35]
	global_load_dwordx4 v[134:137], v[18:19], off
	global_load_dwordx4 v[138:141], v[6:7], off
	v_add_u32_e32 v6, 0, v128
	v_mad_u32_u24 v91, v142, s66, v6
	v_or_b32_sdwa v7, v154, s1 dst_sel:DWORD dst_unused:UNUSED_PAD src0_sel:BYTE_0 src1_sel:DWORD
	v_lshrrev_b32_e32 v145, 4, v7
	v_lshrrev_b32_e32 v7, 3, v7
	v_mad_u32_u24 v144, v142, s69, v6
	s_waitcnt vmcnt(27)
	ds_write2_b64 v91, v[10:11], v[12:13] offset1:1
	v_mad_u32_u24 v10, v142, s66, v181
	v_mad_u32_u24 v11, v142, s69, v182
	v_mad_u32_u24 v12, v142, s66, v183
	v_mad_u32_u24 v13, v142, s69, v184
	v_mad_u32_u24 v146, v145, s66, v6
	v_mad_u32_u24 v148, v145, s69, v6
	v_add_u32_e32 v149, v6, v10
	v_add_u32_e32 v151, v6, v11
	v_add_u32_e32 v152, v6, v12
	v_add_u32_e32 v155, v6, v13
	v_add_u32_e32 v6, 0, v72
	v_mul_u32_u24_e32 v73, 0x88, v156
	v_mul_u32_u24_e32 v90, 0x88, v7
	v_add_u32_e32 v143, 0x4200, v91
	v_add_u32_e32 v147, 0x4200, v146
	v_add_u32_e32 v150, 0x4200, v149
	v_add_u32_e32 v153, 0x4200, v152
	v_add3_u32 v157, v6, v73, s91
	v_add3_u32 v158, v6, v90, s91
	s_waitcnt vmcnt(26)
	ds_write2_b64 v143, v[14:15], v[16:17] offset1:1
	s_waitcnt vmcnt(25)
	ds_write_b128 v144, v[24:27] offset:42496
	s_waitcnt vmcnt(24)
	ds_write2_b64 v146, v[36:37], v[38:39] offset1:1
	s_waitcnt vmcnt(23)
	ds_write2_b64 v147, v[40:41], v[42:43] offset1:1
	s_waitcnt vmcnt(22)
	ds_write_b128 v148, v[44:47] offset:42496
	s_waitcnt vmcnt(21)
	ds_write2_b64 v149, v[48:49], v[50:51] offset1:1
	s_waitcnt vmcnt(20)
	ds_write2_b64 v150, v[52:53], v[54:55] offset1:1
	s_waitcnt vmcnt(19)
	ds_write_b128 v151, v[56:59] offset:42496
	s_waitcnt vmcnt(18)
	ds_write2_b64 v152, v[60:61], v[62:63] offset1:1
	v_add_u32_e32 v6, s93, v128
	s_waitcnt vmcnt(17)
	ds_write2_b64 v153, v[64:65], v[66:67] offset1:1
	v_add_u32_e32 v15, 0xea00, v91
	v_add_u32_e32 v14, s94, v128
	v_add_u32_e32 v10, v6, v10
	v_lshl_add_u64 v[18:19], v[2:3], 0, s[40:41]
	v_lshl_add_u64 v[40:41], v[18:19], 0, v[20:21]
	v_lshl_add_u64 v[52:53], v[18:19], 0, v[22:23]
	s_waitcnt vmcnt(15)
	ds_write_b128 v155, v[68:71] offset:42496
	v_lshl_add_u64 v[68:69], v[4:5], 0, s[40:41]
	v_lshl_add_u64 v[24:25], v[68:69], 0, v[8:9]
	v_lshl_add_u64 v[44:45], v[68:69], 0, v[20:21]
	v_lshl_add_u64 v[56:57], v[68:69], 0, v[22:23]
	s_ashr_i32 s1, s0, 31
	s_waitcnt vmcnt(13)
	ds_write2_b64 v157, v[74:75], v[76:77] offset1:1
	s_lshl_b64 s[14:15], s[0:1], 25
	s_lshl_b32 s12, s99, 8
	s_and_b32 s12, s12, 0x700
	s_waitcnt vmcnt(11)
	ds_write2_b64 v158, v[78:79], v[80:81] offset1:1
	s_waitcnt lgkmcnt(0)
	s_barrier
	s_waitcnt vmcnt(10)
	ds_write2_b64 v15, v[82:83], v[84:85] offset1:1
	v_mad_u32_u24 v15, v142, s66, v6
	ds_write2_b64 v15, v[86:87], v[88:89] offset1:1
	v_mad_u32_u24 v15, v142, s69, v14
	ds_write_b128 v15, v[92:95]
	v_add_u32_e32 v15, 0xea00, v146
	s_waitcnt vmcnt(9)
	ds_write2_b64 v15, v[96:97], v[98:99] offset1:1
	v_mad_u32_u24 v15, v145, s66, v6
	ds_write2_b64 v15, v[100:101], v[102:103] offset1:1
	v_mad_u32_u24 v15, v145, s69, v14
	s_waitcnt vmcnt(8)
	ds_write_b128 v15, v[104:107]
	v_add_u32_e32 v15, 0xea00, v149
	s_waitcnt vmcnt(7)
	ds_write2_b64 v10, v[112:113], v[114:115] offset1:1
	v_add_u32_e32 v10, v14, v11
	v_add_u32_e32 v6, v6, v12
	s_waitcnt vmcnt(5)
	ds_write2_b64 v15, v[108:109], v[110:111] offset1:1
	s_waitcnt vmcnt(4)
	ds_write_b128 v10, v[116:119]
	v_add_u32_e32 v10, 0xea00, v152
	s_waitcnt vmcnt(3)
	ds_write2_b64 v6, v[124:125], v[126:127] offset1:1
	v_add_u32_e32 v6, v14, v13
	ds_write2_b64 v10, v[120:121], v[122:123] offset1:1
	s_waitcnt vmcnt(2)
	ds_write_b128 v6, v[130:133]
	v_add_u32_e32 v6, s95, v72
	v_mad_u32_u24 v10, v156, s90, v6
	v_mad_u32_u24 v6, v7, s90, v6
	s_waitcnt vmcnt(1)
	ds_write2_b64 v10, v[134:135], v[136:137] offset1:1
	s_waitcnt vmcnt(0)
	ds_write2_b64 v6, v[138:139], v[140:141] offset1:1
	v_lshl_add_u64 v[6:7], v[0:1], 0, s[40:41]
	v_lshl_add_u64 v[10:11], v[6:7], 0, v[8:9]
	v_lshl_add_u64 v[14:15], v[18:19], 0, v[8:9]
	v_lshl_add_u64 v[36:37], v[6:7], 0, v[20:21]
	v_lshl_add_u64 v[48:49], v[6:7], 0, v[22:23]
	v_lshl_add_u64 v[6:7], v[6:7], 0, v[28:29]
	global_load_dwordx4 v[10:13], v[10:11], off
	v_bfe_u32 v84, v154, 2, 6
	global_load_dwordx4 v[14:17], v[14:15], off
	s_nop 0
	global_load_dwordx4 v[24:27], v[24:25], off
	s_nop 0
	global_load_dwordx4 v[36:39], v[36:37], off
	v_mov_b32_e32 v83, v129
	global_load_dwordx4 v[40:43], v[40:41], off
	s_nop 0
	global_load_dwordx4 v[44:47], v[44:45], off
	s_nop 0
	global_load_dwordx4 v[48:51], v[48:49], off
	s_lshl_b64 s[0:1], s[0:1], 23
	global_load_dwordx4 v[52:55], v[52:53], off
	s_nop 0
	global_load_dwordx4 v[56:59], v[56:57], off
	s_nop 0
	global_load_dwordx4 v[60:63], v[6:7], off
	v_lshl_add_u64 v[6:7], v[18:19], 0, v[28:29]
	global_load_dwordx4 v[64:67], v[6:7], off
	v_lshl_add_u64 v[6:7], v[68:69], 0, v[28:29]
	global_load_dwordx4 v[68:71], v[6:7], off
	v_lshl_add_u64 v[6:7], v[30:31], 0, s[38:39]
	v_lshl_add_u64 v[18:19], v[6:7], 0, v[32:33]
	v_lshl_add_u64 v[6:7], v[6:7], 0, v[34:35]
	global_load_dwordx4 v[74:77], v[18:19], off
	global_load_dwordx4 v[78:81], v[6:7], off
	s_waitcnt lgkmcnt(0)
	s_barrier
	s_waitcnt vmcnt(13)
	ds_write2_b64 v91, v[10:11], v[12:13] offset1:1
	s_waitcnt vmcnt(12)
	ds_write2_b64 v143, v[14:15], v[16:17] offset1:1
	s_waitcnt vmcnt(11)
	ds_write_b128 v144, v[24:27] offset:42496
	s_waitcnt vmcnt(10)
	ds_write2_b64 v146, v[36:37], v[38:39] offset1:1
	s_waitcnt vmcnt(9)
	ds_write2_b64 v147, v[40:41], v[42:43] offset1:1
	s_waitcnt vmcnt(8)
	ds_write_b128 v148, v[44:47] offset:42496
	s_waitcnt vmcnt(7)
	ds_write2_b64 v149, v[48:49], v[50:51] offset1:1
	s_waitcnt vmcnt(6)
	ds_write2_b64 v150, v[52:53], v[54:55] offset1:1
	s_waitcnt vmcnt(5)
	ds_write_b128 v151, v[56:59] offset:42496
	s_waitcnt vmcnt(4)
	ds_write2_b64 v152, v[60:61], v[62:63] offset1:1
	s_waitcnt vmcnt(3)
	ds_write2_b64 v153, v[64:65], v[66:67] offset1:1
	s_waitcnt vmcnt(2)
	ds_write_b128 v155, v[68:71] offset:42496
	s_waitcnt vmcnt(1)
	ds_write2_b64 v157, v[74:75], v[76:77] offset1:1
	s_waitcnt vmcnt(0)
	ds_write2_b64 v158, v[78:79], v[80:81] offset1:1
	v_lshl_add_u64 v[36:37], v[0:1], 0, s[42:43]
	v_lshl_add_u64 v[38:39], v[2:3], 0, s[42:43]
	v_lshl_add_u64 v[60:61], v[4:5], 0, s[42:43]
	v_lshlrev_b32_e32 v6, 5, v154
	v_lshl_add_u64 v[0:1], v[36:37], 0, v[8:9]
	v_lshl_add_u64 v[4:5], v[38:39], 0, v[8:9]
	v_lshl_add_u64 v[8:9], v[60:61], 0, v[8:9]
	v_lshl_add_u64 v[12:13], v[36:37], 0, v[20:21]
	v_lshl_add_u64 v[16:17], v[38:39], 0, v[20:21]
	v_lshl_add_u64 v[20:21], v[60:61], 0, v[20:21]
	v_lshl_add_u64 v[40:41], v[36:37], 0, v[22:23]
	v_and_b32_e32 v85, 0x60, v6
	global_load_dwordx4 v[0:3], v[0:1], off
	v_lshl_or_b32 v80, v84, 14, s14
	global_load_dwordx4 v[4:7], v[4:5], off
	s_nop 0
	global_load_dwordx4 v[8:11], v[8:9], off
	s_nop 0
	global_load_dwordx4 v[12:15], v[12:13], off
	v_mov_b32_e32 v81, s15
	global_load_dwordx4 v[16:19], v[16:17], off
	s_nop 0
	global_load_dwordx4 v[24:27], v[20:21], off
	s_nop 0
	global_load_dwordx4 v[40:43], v[40:41], off
	v_lshl_add_u64 v[20:21], v[38:39], 0, v[22:23]
	global_load_dwordx4 v[44:47], v[20:21], off
	v_lshl_add_u64 v[20:21], v[60:61], 0, v[22:23]
	v_lshl_add_u64 v[22:23], v[36:37], 0, v[28:29]
	global_load_dwordx4 v[48:51], v[20:21], off
	global_load_dwordx4 v[52:55], v[22:23], off
	v_lshl_add_u64 v[20:21], v[38:39], 0, v[28:29]
	global_load_dwordx4 v[56:59], v[20:21], off
	v_lshl_add_u64 v[20:21], v[60:61], 0, v[28:29]
	global_load_dwordx4 v[60:63], v[20:21], off
	v_lshl_add_u64 v[20:21], v[30:31], 0, s[46:47]
	v_lshl_add_u64 v[22:23], v[20:21], 0, v[32:33]
	v_lshl_add_u64 v[20:21], v[20:21], 0, v[34:35]
	global_load_dwordx4 v[64:67], v[22:23], off
	global_load_dwordx4 v[68:71], v[20:21], off
	v_lshl_add_u64 v[20:21], s[28:29], 0, v[80:81]
	v_lshlrev_b32_e32 v82, 1, v85
	v_lshl_add_u64 v[20:21], v[20:21], 0, s[12:13]
	v_lshl_add_u64 v[20:21], v[20:21], 0, v[82:83]
	v_lshl_add_u64 v[36:37], v[20:21], 0, s[48:49]
	v_add_co_u32_e32 v20, vcc, s96, v20
	v_mul_u32_u24_e32 v74, 0x110, v84
	s_nop 0
	v_addc_co_u32_e32 v21, vcc, 0, v21, vcc
	global_load_dwordx4 v[32:35], v[20:21], off offset:2048
	s_nop 0
	global_load_dwordx4 v[20:23], v[36:37], off offset:48
	global_load_dwordx4 v[28:31], v[36:37], off offset:32
	s_nop 0
	global_load_dwordx4 v[36:39], v[36:37], off offset:16
	v_add3_u32 v96, s92, v74, v82
	v_and_b32_e32 v77, 15, v154
	v_lshlrev_b32_e32 v82, 6, v154
	v_and_b32_e32 v75, 7, v154
	v_lshlrev_b32_e32 v76, 8, v142
	v_lshlrev_b32_e32 v77, 4, v77
	v_and_b32_e32 v82, 0xc0, v82
	s_add_i32 s14, 0, 0x25c00
	v_lshlrev_b32_e32 v74, 7, v156
	v_lshlrev_b32_e32 v75, 4, v75
	v_or3_b32 v78, s33, v76, v77
	v_mov_b32_e32 v79, s3
	v_or3_b32 v80, v80, s12, v82
	v_lshl_or_b32 v83, v84, 12, s0
	s_mov_b32 s54, 3
	v_mul_u32_u24_e32 v91, 0x108, v142
	v_mul_u32_u24_e32 v92, 0x110, v142
	v_mul_u32_u24_e32 v93, 0x108, v145
	v_mul_u32_u24_e32 v94, 0x110, v145
	v_lshl_add_u32 v95, v85, 2, s14
	v_or3_b32 v74, s4, v74, v75
	v_mov_b32_e32 v75, s5
	v_lshl_add_u64 v[76:77], s[28:29], 0, v[78:79]
	v_lshl_add_u64 v[78:79], s[26:27], 0, v[78:79]
	v_lshl_add_u64 v[80:81], s[18:19], 0, v[80:81]
	global_load_dwordx4 v[196:199], v[80:81], off offset:16
	global_load_dwordx4 v[200:203], v[80:81], off
	global_load_dwordx4 v[204:207], v[80:81], off offset:-16
	global_load_dwordx4 v[208:211], v[80:81], off offset:-32
	v_or3_b32 v82, v83, s12, v82
	v_mov_b32_e32 v83, s1
	s_mov_b64 s[0:1], 0
	s_branch .LBB0_558

.LBB0_560:
	s_waitcnt vmcnt(4)
	s_cmp_gt_u32 s12, 30
	s_cbranch_scc1 .LBB0_562
	s_waitcnt vmcnt(6)
	v_lshl_add_u64 v[60:61], v[76:77], 0, s[0:1]
	v_add_co_u32_e32 v0, vcc, 0x2110000, v60
	v_lshl_add_u64 v[56:57], v[78:79], 0, s[0:1]
	s_nop 0
	v_addc_co_u32_e32 v1, vcc, 0, v61, vcc
	v_add_co_u32_e32 v4, vcc, 0x4010000, v56
	s_waitcnt vmcnt(5)
	v_lshl_add_u64 v[64:65], s[26:27], 0, v[74:75]
	v_addc_co_u32_e32 v5, vcc, 0, v57, vcc
	v_add_co_u32_e32 v8, vcc, 0x1b910000, v60
	global_load_dwordx4 v[0:3], v[0:1], off
	s_nop 0
	v_addc_co_u32_e32 v9, vcc, 0, v61, vcc
	v_add_co_u32_e32 v12, vcc, 0x2111000, v60
	global_load_dwordx4 v[4:7], v[4:5], off
	s_nop 0
	v_addc_co_u32_e32 v13, vcc, 0, v61, vcc
	v_add_co_u32_e32 v16, vcc, 0x4011000, v56
	global_load_dwordx4 v[8:11], v[8:9], off
	s_nop 0
	global_load_dwordx4 v[12:15], v[12:13], off
	v_addc_co_u32_e32 v17, vcc, 0, v57, vcc
	v_add_co_u32_e32 v24, vcc, 0x1b911000, v60
	global_load_dwordx4 v[16:19], v[16:17], off
	s_nop 0
	v_addc_co_u32_e32 v25, vcc, 0, v61, vcc
	v_add_co_u32_e32 v40, vcc, 0x2112000, v60
	s_nop 1
	v_addc_co_u32_e32 v41, vcc, 0, v61, vcc
	v_add_co_u32_e32 v44, vcc, 0x4012000, v56
	global_load_dwordx4 v[24:27], v[24:25], off
	s_nop 0
	global_load_dwordx4 v[40:43], v[40:41], off
	v_addc_co_u32_e32 v45, vcc, 0, v57, vcc
	v_add_co_u32_e32 v48, vcc, 0x1b912000, v60
	global_load_dwordx4 v[44:47], v[44:45], off
	s_nop 0
	v_addc_co_u32_e32 v49, vcc, 0, v61, vcc
	v_add_co_u32_e32 v52, vcc, 0x2113000, v60
	s_nop 1
	v_addc_co_u32_e32 v53, vcc, 0, v61, vcc
	v_add_co_u32_e32 v56, vcc, 0x4013000, v56
	global_load_dwordx4 v[48:51], v[48:49], off
	s_nop 0
	global_load_dwordx4 v[52:55], v[52:53], off
	v_addc_co_u32_e32 v57, vcc, 0, v57, vcc
	v_add_co_u32_e32 v60, vcc, 0x1b913000, v60
	global_load_dwordx4 v[56:59], v[56:57], off
	s_nop 0
	v_addc_co_u32_e32 v61, vcc, 0, v61, vcc
	v_add_co_u32_e32 v66, vcc, 0x6108000, v64
	global_load_dwordx4 v[60:63], v[60:61], off
	s_nop 0
	v_addc_co_u32_e32 v67, vcc, 0, v65, vcc
	s_waitcnt vmcnt(16)
	v_add_co_u32_e32 v68, vcc, 0x6109000, v64
	s_nop 1
	v_addc_co_u32_e32 v69, vcc, 0, v65, vcc
	global_load_dwordx4 v[64:67], v[66:67], off
	s_nop 0
	global_load_dwordx4 v[68:71], v[68:69], off

.LBB0_566:
	s_andn2_b64 vcc, exec, s[4:5]
	s_cbranch_vccnz .LBB0_557
	s_cmp_gt_u32 s12, 30
	s_cbranch_scc1 .Lscg_w4
	s_waitcnt vmcnt(18)
	s_branch .Lscg_mv
.Lscg_w4:
	s_waitcnt vmcnt(4)
.Lscg_mv:
	v_mov_b64_e32 v[20:21], v[196:197]
	v_mov_b64_e32 v[22:23], v[198:199]
	v_mov_b64_e32 v[28:29], v[200:201]
	v_mov_b64_e32 v[30:31], v[202:203]
	v_mov_b64_e32 v[36:37], v[204:205]
	v_mov_b64_e32 v[38:39], v[206:207]
	v_mov_b64_e32 v[32:33], v[208:209]
	v_mov_b64_e32 v[34:35], v[210:211]
	s_cmp_gt_u32 s12, 31
	s_cbranch_scc1 .LBB0_557
	v_lshl_add_u64 v[212:213], v[80:81], 0, s[50:51]
	global_load_dwordx4 v[196:199], v[212:213], off offset:16
	global_load_dwordx4 v[200:203], v[212:213], off
	global_load_dwordx4 v[204:207], v[212:213], off offset:-16
	global_load_dwordx4 v[208:211], v[212:213], off offset:-32
	s_branch .LBB0_557
